# adds: attention PV V-fragment ds_read_b64_tr_b16 reads hoisted above the exp block into registers dead there (v98-v129), MFMAs back-to-back
# speedup vs baseline: 1.0106x; 1.0106x over previous
.LBB0_195:
	v_lshl_add_u32 v2, v179, 1, s87
	v_add3_u32 v2, v2, v237, v184
	ds_read_b64_tr_b16 v[98:99], v2 offset:9216
	ds_read_b64_tr_b16 v[100:101], v2 offset:10368
	ds_read_b64_tr_b16 v[102:103], v2 offset:9280
	ds_read_b64_tr_b16 v[104:105], v2 offset:10432
	ds_read_b64_tr_b16 v[106:107], v2 offset:11520
	ds_read_b64_tr_b16 v[108:109], v2 offset:12672
	ds_read_b64_tr_b16 v[110:111], v2 offset:11584
	ds_read_b64_tr_b16 v[112:113], v2 offset:12736
	ds_read_b64_tr_b16 v[114:115], v2 offset:13824
	ds_read_b64_tr_b16 v[116:117], v2 offset:14976
	ds_read_b64_tr_b16 v[118:119], v2 offset:13888
	ds_read_b64_tr_b16 v[120:121], v2 offset:15040
	ds_read_b64_tr_b16 v[122:123], v2 offset:16128
	ds_read_b64_tr_b16 v[124:125], v2 offset:17280
	ds_read_b64_tr_b16 v[126:127], v2 offset:16192
	ds_read_b64_tr_b16 v[128:129], v2 offset:17344
	v_exp_f32_e32 v2, v82
	v_exp_f32_e32 v4, v66
	v_exp_f32_e32 v7, v83
	v_exp_f32_e32 v14, v67
	v_exp_f32_e32 v15, v68
	v_add_f32_e32 v6, v4, v2
	v_add_f32_e32 v6, 0, v6
	v_add_f32_e32 v8, v14, v7
	v_add_f32_e32 v6, v8, v6
	v_exp_f32_e32 v8, v84
	v_exp_f32_e32 v16, v69
	v_exp_f32_e32 v17, v70
	v_exp_f32_e32 v66, v71
	v_add_f32_e32 v9, v15, v8
	v_add_f32_e32 v6, v9, v6
	v_exp_f32_e32 v9, v85
	v_exp_f32_e32 v67, v72
	v_exp_f32_e32 v68, v73
	v_exp_f32_e32 v70, v74
	v_add_f32_e32 v10, v16, v9
	v_add_f32_e32 v6, v10, v6
	v_exp_f32_e32 v10, v86
	v_exp_f32_e32 v72, v75
	v_exp_f32_e32 v74, v76
	v_exp_f32_e32 v76, v77
	v_add_f32_e32 v11, v17, v10
	v_add_f32_e32 v6, v11, v6
	v_exp_f32_e32 v11, v87
	v_exp_f32_e32 v78, v78
	v_exp_f32_e32 v79, v79
	v_exp_f32_e32 v80, v80
	v_add_f32_e32 v12, v66, v11
	v_add_f32_e32 v6, v12, v6
	v_exp_f32_e32 v12, v88
	v_exp_f32_e32 v81, v81
	v_subrev_u32_e32 v185, 64, v185
	v_add_u32_e32 v187, 0x7c, v187
	v_add_f32_e32 v13, v67, v12
	v_add_f32_e32 v6, v13, v6
	v_exp_f32_e32 v13, v89
	s_cmp_lg_u32 s84, s2
	v_add_f32_e32 v69, v68, v13
	v_add_f32_e32 v6, v69, v6
	v_exp_f32_e32 v69, v90
	s_nop 0
	v_add_f32_e32 v71, v70, v69
	v_add_f32_e32 v6, v71, v6
	v_exp_f32_e32 v71, v91
	s_nop 0
	v_add_f32_e32 v73, v72, v71
	v_add_f32_e32 v6, v73, v6
	v_exp_f32_e32 v73, v92
	s_nop 0
	v_add_f32_e32 v75, v74, v73
	v_add_f32_e32 v6, v75, v6
	v_exp_f32_e32 v75, v93
	s_nop 0
	v_add_f32_e32 v77, v76, v75
	v_add_f32_e32 v6, v77, v6
	v_exp_f32_e32 v77, v94
	s_nop 0
	v_add_f32_e32 v82, v78, v77
	v_add_f32_e32 v6, v82, v6
	v_exp_f32_e32 v82, v95
	s_nop 0
	v_add_f32_e32 v83, v79, v82
	v_add_f32_e32 v6, v83, v6
	v_exp_f32_e32 v83, v96
	s_nop 0
	v_add_f32_e32 v84, v80, v83
	v_add_f32_e32 v6, v84, v6
	v_exp_f32_e32 v84, v97
	s_nop 0
	v_add_f32_e32 v85, v81, v84
	v_add_f32_e32 v6, v85, v6
	v_lshl_add_u32 v85, v179, 1, s87
	v_add_f32_e32 v5, v5, v6
	v_cvt_pk_bf16_f32 v6, v2, v7
	v_add3_u32 v2, v85, v237, v184
	v_cvt_pk_bf16_f32 v7, v8, v9
	v_cvt_pk_bf16_f32 v8, v10, v11
	v_cvt_pk_bf16_f32 v9, v12, v13
	s_waitcnt lgkmcnt(0)
	v_mfma_f32_32x32x16_bf16 v[18:33], v[98:101], v[6:9], v[18:33]
	s_waitcnt lgkmcnt(0)
	v_mfma_f32_32x32x16_bf16 v[34:49], v[102:105], v[6:9], v[34:49]
	v_cvt_pk_bf16_f32 v6, v69, v71
	v_cvt_pk_bf16_f32 v7, v73, v75
	v_cvt_pk_bf16_f32 v8, v77, v82
	v_cvt_pk_bf16_f32 v9, v83, v84
	s_waitcnt lgkmcnt(0)
	s_nop 0
	v_mfma_f32_32x32x16_bf16 v[18:33], v[106:109], v[6:9], v[18:33]
	s_waitcnt lgkmcnt(0)
	v_mfma_f32_32x32x16_bf16 v[34:49], v[110:113], v[6:9], v[34:49]
	v_cvt_pk_bf16_f32 v6, v4, v14
	v_cvt_pk_bf16_f32 v7, v15, v16
	v_cvt_pk_bf16_f32 v8, v17, v66
	v_cvt_pk_bf16_f32 v9, v67, v68
	s_waitcnt lgkmcnt(0)
	s_nop 0
	v_mfma_f32_32x32x16_bf16 v[18:33], v[114:117], v[6:9], v[18:33]
	s_waitcnt lgkmcnt(0)
	v_mfma_f32_32x32x16_bf16 v[34:49], v[118:121], v[6:9], v[34:49]
	v_cvt_pk_bf16_f32 v6, v70, v72
	v_cvt_pk_bf16_f32 v7, v74, v76
	v_cvt_pk_bf16_f32 v8, v78, v79
	v_cvt_pk_bf16_f32 v9, v80, v81
	s_waitcnt lgkmcnt(0)
	s_nop 0
	v_mfma_f32_32x32x16_bf16 v[18:33], v[122:125], v[6:9], v[18:33]
	s_waitcnt lgkmcnt(0)
	s_barrier
	v_mfma_f32_32x32x16_bf16 v[34:49], v[126:129], v[6:9], v[34:49]
	s_cbranch_scc0 .LBB0_197
	s_mov_b32 s86, s2
	s_branch .LBB0_120

.LBB0_289:
	v_lshl_add_u32 v2, v214, 1, s2
	v_add3_u32 v2, v2, v198, v218
	ds_read_b64_tr_b16 v[98:99], v2 offset:13312
	ds_read_b64_tr_b16 v[100:101], v2 offset:14464
	ds_read_b64_tr_b16 v[102:103], v2 offset:13376
	ds_read_b64_tr_b16 v[104:105], v2 offset:14528
	ds_read_b64_tr_b16 v[106:107], v2 offset:15616
	ds_read_b64_tr_b16 v[108:109], v2 offset:16768
	ds_read_b64_tr_b16 v[110:111], v2 offset:15680
	ds_read_b64_tr_b16 v[112:113], v2 offset:16832
	ds_read_b64_tr_b16 v[114:115], v2 offset:17920
	ds_read_b64_tr_b16 v[116:117], v2 offset:19072
	ds_read_b64_tr_b16 v[118:119], v2 offset:17984
	ds_read_b64_tr_b16 v[120:121], v2 offset:19136
	ds_read_b64_tr_b16 v[122:123], v2 offset:20224
	ds_read_b64_tr_b16 v[124:125], v2 offset:21376
	ds_read_b64_tr_b16 v[126:127], v2 offset:20288
	ds_read_b64_tr_b16 v[128:129], v2 offset:21440
	v_exp_f32_e32 v2, v82
	v_exp_f32_e32 v4, v66
	v_exp_f32_e32 v7, v83
	v_exp_f32_e32 v14, v67
	v_exp_f32_e32 v15, v68
	v_add_f32_e32 v6, v4, v2
	v_add_f32_e32 v6, 0, v6
	v_add_f32_e32 v8, v14, v7
	v_add_f32_e32 v6, v8, v6
	v_exp_f32_e32 v8, v84
	v_exp_f32_e32 v16, v69
	v_exp_f32_e32 v17, v70
	v_exp_f32_e32 v66, v71
	v_add_f32_e32 v9, v15, v8
	v_add_f32_e32 v6, v9, v6
	v_exp_f32_e32 v9, v85
	v_exp_f32_e32 v67, v72
	v_exp_f32_e32 v68, v73
	v_exp_f32_e32 v70, v74
	v_add_f32_e32 v10, v16, v9
	v_add_f32_e32 v6, v10, v6
	v_exp_f32_e32 v10, v86
	v_exp_f32_e32 v72, v75
	v_exp_f32_e32 v74, v76
	v_exp_f32_e32 v76, v77
	v_add_f32_e32 v11, v17, v10
	v_add_f32_e32 v6, v11, v6
	v_exp_f32_e32 v11, v87
	v_exp_f32_e32 v78, v78
	v_exp_f32_e32 v79, v79
	v_exp_f32_e32 v80, v80
	v_add_f32_e32 v12, v66, v11
	v_add_f32_e32 v6, v12, v6
	v_exp_f32_e32 v12, v88
	v_exp_f32_e32 v81, v81
	v_subrev_u32_e32 v219, 64, v219
	v_add_u32_e32 v221, 0x7c, v221
	v_add_f32_e32 v13, v67, v12
	v_add_f32_e32 v6, v13, v6
	v_exp_f32_e32 v13, v89
	s_cmp_lg_u32 s76, s3
	v_add_f32_e32 v69, v68, v13
	v_add_f32_e32 v6, v69, v6
	v_exp_f32_e32 v69, v90
	s_nop 0
	v_add_f32_e32 v71, v70, v69
	v_add_f32_e32 v6, v71, v6
	v_exp_f32_e32 v71, v91
	s_nop 0
	v_add_f32_e32 v73, v72, v71
	v_add_f32_e32 v6, v73, v6
	v_exp_f32_e32 v73, v92
	s_nop 0
	v_add_f32_e32 v75, v74, v73
	v_add_f32_e32 v6, v75, v6
	v_exp_f32_e32 v75, v93
	s_nop 0
	v_add_f32_e32 v77, v76, v75
	v_add_f32_e32 v6, v77, v6
	v_exp_f32_e32 v77, v94
	s_nop 0
	v_add_f32_e32 v82, v78, v77
	v_add_f32_e32 v6, v82, v6
	v_exp_f32_e32 v82, v95
	s_nop 0
	v_add_f32_e32 v83, v79, v82
	v_add_f32_e32 v6, v83, v6
	v_exp_f32_e32 v83, v96
	s_nop 0
	v_add_f32_e32 v84, v80, v83
	v_add_f32_e32 v6, v84, v6
	v_exp_f32_e32 v84, v97
	s_nop 0
	v_add_f32_e32 v85, v81, v84
	v_add_f32_e32 v6, v85, v6
	v_lshl_add_u32 v85, v214, 1, s2
	v_add_f32_e32 v5, v5, v6
	v_cvt_pk_bf16_f32 v6, v2, v7
	v_add3_u32 v2, v85, v198, v218
	v_cvt_pk_bf16_f32 v7, v8, v9
	v_cvt_pk_bf16_f32 v8, v10, v11
	v_cvt_pk_bf16_f32 v9, v12, v13
	s_waitcnt lgkmcnt(0)
	v_mfma_f32_32x32x16_bf16 v[18:33], v[98:101], v[6:9], v[18:33]
	s_waitcnt lgkmcnt(0)
	v_mfma_f32_32x32x16_bf16 v[34:49], v[102:105], v[6:9], v[34:49]
	v_cvt_pk_bf16_f32 v6, v69, v71
	v_cvt_pk_bf16_f32 v7, v73, v75
	v_cvt_pk_bf16_f32 v8, v77, v82
	v_cvt_pk_bf16_f32 v9, v83, v84
	s_waitcnt lgkmcnt(0)
	s_nop 0
	v_mfma_f32_32x32x16_bf16 v[18:33], v[106:109], v[6:9], v[18:33]
	s_waitcnt lgkmcnt(0)
	v_mfma_f32_32x32x16_bf16 v[34:49], v[110:113], v[6:9], v[34:49]
	v_cvt_pk_bf16_f32 v6, v4, v14
	v_cvt_pk_bf16_f32 v7, v15, v16
	v_cvt_pk_bf16_f32 v8, v17, v66
	v_cvt_pk_bf16_f32 v9, v67, v68
	s_waitcnt lgkmcnt(0)
	s_nop 0
	v_mfma_f32_32x32x16_bf16 v[18:33], v[114:117], v[6:9], v[18:33]
	s_waitcnt lgkmcnt(0)
	v_mfma_f32_32x32x16_bf16 v[34:49], v[118:121], v[6:9], v[34:49]
	v_cvt_pk_bf16_f32 v6, v70, v72
	v_cvt_pk_bf16_f32 v7, v74, v76
	v_cvt_pk_bf16_f32 v8, v78, v79
	v_cvt_pk_bf16_f32 v9, v80, v81
	s_waitcnt lgkmcnt(0)
	s_nop 0
	v_mfma_f32_32x32x16_bf16 v[18:33], v[122:125], v[6:9], v[18:33]
	s_waitcnt lgkmcnt(0)
	s_barrier
	v_mfma_f32_32x32x16_bf16 v[34:49], v[126:129], v[6:9], v[34:49]
	s_cbranch_scc0 .LBB0_71
	s_mov_b32 s77, s3
	s_branch .LBB0_214
